# HGRN2 pass A state update: operand and decay LDS reads of the 8 MFMA steps issued as one batch with counted waits
# speedup vs baseline: 1.0033x; 1.0033x over previous
.LBB0_242:
	s_waitcnt lgkmcnt(0)
	s_barrier
	ds_read_b128 v[146:149], v119
	ds_read_b128 v[150:153], v119 offset:64
	ds_read_b128 v[154:157], v119 offset:128
	ds_read_b128 v[56:59], v119 offset:192
	ds_read_b128 v[52:55], v120
	ds_read_b128 v[48:51], v120 offset:64
	ds_read_b128 v[44:47], v120 offset:128
	ds_read_b128 v[40:43], v120 offset:192
	ds_read_b128 v[158:161], v121 offset:8704
	ds_read_b128 v[162:165], v121 offset:13056
	ds_read_b128 v[184:187], v121 offset:8768
	ds_read_b128 v[188:191], v121 offset:13120
	s_waitcnt lgkmcnt(3)
	v_mfma_f32_16x16x32_bf16 v[166:169], v[158:161], v[146:149], 0
	v_add_f32_e32 v133, v133, v2
	s_add_i32 s20, s20, -1
	s_cmp_eq_u32 s20, 0
	s_waitcnt lgkmcnt(2)
	v_mfma_f32_16x16x32_bf16 v[162:165], v[162:165], v[52:55], 0
	v_mfma_f32_16x16x32_bf16 v[158:161], v[158:161], v[52:55], 0
	s_waitcnt lgkmcnt(0)
	v_mfma_f32_16x16x32_bf16 v[162:165], v[188:191], v[48:51], v[162:165]
	ds_read_b128 v[188:191], v121 offset:8832
	ds_read_b128 v[192:195], v121 offset:13184
	v_mfma_f32_16x16x32_bf16 v[166:169], v[184:187], v[150:153], v[166:169]
	v_mfma_f32_16x16x32_bf16 v[158:161], v[184:187], v[48:51], v[158:161]
	s_waitcnt lgkmcnt(0)
	v_mfma_f32_16x16x32_bf16 v[162:165], v[192:195], v[44:47], v[162:165]
	ds_read_b128 v[192:195], v121 offset:8896
	ds_read_b128 v[196:199], v121 offset:13248
	v_mfma_f32_16x16x32_bf16 v[166:169], v[188:191], v[154:157], v[166:169]
	v_mfma_f32_16x16x32_bf16 v[158:161], v[188:191], v[44:47], v[158:161]
	s_waitcnt lgkmcnt(1)
	v_mfma_f32_16x16x32_bf16 v[166:169], v[192:195], v[56:59], v[166:169]
	s_waitcnt lgkmcnt(0)
	v_mfma_f32_16x16x32_bf16 v[162:165], v[196:199], v[40:43], v[162:165]
	v_mfma_f32_16x16x32_bf16 v[158:161], v[192:195], v[40:43], v[158:161]
	s_nop 4
	v_cndmask_b32_e64 v0, v166, 0, s[12:13]
	s_nop 0
	v_cndmask_b32_e64 v145, v162, 0, s[12:13]
	v_cndmask_b32_e64 v1, 0, v167, s[14:15]
	v_cndmask_b32_e64 v162, 0, v163, s[14:15]
	v_cndmask_b32_e64 v2, v168, 0, s[16:17]
	v_cndmask_b32_e64 v163, v164, 0, s[16:17]
	v_cndmask_b32_e64 v164, v169, 0, s[18:19]
	v_cndmask_b32_e64 v165, v165, 0, s[18:19]
	v_cvt_pk_bf16_f32 v0, v0, v1
	v_cvt_pk_bf16_f32 v1, v2, v164
	v_cvt_pk_bf16_f32 v158, v158, v159
	v_cvt_pk_bf16_f32 v159, v160, v161
	v_cvt_pk_bf16_f32 v160, v145, v162
	v_cvt_pk_bf16_f32 v161, v163, v165
	ds_read2_b64 v[162:165], v126 offset0:128 offset1:132
	ds_read_b128 v[166:169], v122 offset:37888
	ds_read_b128 v[184:187], v122 offset:37952
	s_waitcnt lgkmcnt(1)
	v_mfma_f32_16x16x32_bf16 v[146:149], v[166:169], v[146:149], 0
	v_mov_b32_e32 v2, v3
	s_waitcnt lgkmcnt(0)
	v_mfma_f32_16x16x32_bf16 v[146:149], v[184:187], v[150:153], v[146:149]
	ds_read_b128 v[150:153], v122 offset:38016
	v_mfma_f32_16x16x32_bf16 v[52:55], v[166:169], v[52:55], 0
	s_waitcnt lgkmcnt(0)
	v_mfma_f32_16x16x32_bf16 v[146:149], v[150:153], v[154:157], v[146:149]
	ds_read_b128 v[154:157], v122 offset:38080
	v_mfma_f32_16x16x32_bf16 v[48:51], v[184:187], v[48:51], v[52:55]
	v_mfma_f32_16x16x32_bf16 v[44:47], v[150:153], v[44:47], v[48:51]
	s_waitcnt lgkmcnt(0)
	v_mfma_f32_16x16x32_bf16 v[56:59], v[154:157], v[56:59], v[146:149]
	v_mfma_f32_16x16x32_bf16 v[40:43], v[154:157], v[40:43], v[44:47]
	v_mfma_f32_16x16x32_bf16 v[56:59], v[162:165], v[0:3], v[56:59]
	v_lshl_add_u64 v[0:1], v[86:87], 0, s[54:55]
	v_mfma_f32_16x16x32_bf16 v[40:43], v[162:165], v[158:161], v[40:43]
	s_nop 5
	global_store_dwordx4 v[0:1], v[56:59], off
	v_lshl_add_u64 v[0:1], v[84:85], 0, s[54:55]
	global_store_dwordx4 v[0:1], v[40:43], off
	v_add_u32_e32 v0, v97, v96
	ds_read_b128 v[40:43], v0 offset:27648
	ds_read_b128 v[44:47], v123 offset:17408
	ds_read_b32 v208, v99
	ds_read_b128 v[200:203], v123 offset:18688
	ds_read_b32 v209, v100
	ds_read_b128 v[204:207], v123 offset:19968
	ds_read_b32 v216, v101
	ds_read_b128 v[230:233], v123 offset:21248
	ds_read_b32 v217, v102
	ds_read_b128 v[234:237], v123 offset:22528
	ds_read_b32 v224, v103
	ds_read_b128 v[238:241], v123 offset:23808
	ds_read_b32 v225, v104
	ds_read_b128 v[242:245], v123 offset:25088
	ds_read_b32 v250, v105
	s_waitcnt lgkmcnt(12)
	ds_read_b128 v[246:249], v123 offset:26368
	ds_read_b32 v251, v106
	v_pk_mul_f32 v[10:11], v[10:11], v[208:209] op_sel_hi:[1,0]
	v_pk_mul_f32 v[8:9], v[8:9], v[208:209] op_sel_hi:[1,0]
	s_nop 1
	v_mfma_f32_16x16x32_bf16 v[8:11], v[40:43], v[44:47], v[8:11]
	s_waitcnt lgkmcnt(12)
	v_pk_mul_f32 v[14:15], v[14:15], v[208:209] op_sel:[0,1] op_sel_hi:[1,1]
	v_pk_mul_f32 v[12:13], v[12:13], v[208:209] op_sel:[0,1] op_sel_hi:[1,1]
	s_nop 1
	v_mfma_f32_16x16x32_bf16 v[12:15], v[40:43], v[200:203], v[12:15]
	s_waitcnt lgkmcnt(10)
	v_pk_mul_f32 v[18:19], v[18:19], v[216:217] op_sel_hi:[1,0]
	v_pk_mul_f32 v[16:17], v[16:17], v[216:217] op_sel_hi:[1,0]
	s_nop 1
	v_mfma_f32_16x16x32_bf16 v[16:19], v[40:43], v[204:207], v[16:19]
	s_waitcnt lgkmcnt(8)
	v_pk_mul_f32 v[22:23], v[22:23], v[216:217] op_sel:[0,1] op_sel_hi:[1,1]
	v_pk_mul_f32 v[20:21], v[20:21], v[216:217] op_sel:[0,1] op_sel_hi:[1,1]
	s_nop 1
	v_mfma_f32_16x16x32_bf16 v[20:23], v[40:43], v[230:233], v[20:23]
	s_waitcnt lgkmcnt(6)
	v_pk_mul_f32 v[26:27], v[26:27], v[224:225] op_sel_hi:[1,0]
	v_pk_mul_f32 v[24:25], v[24:25], v[224:225] op_sel_hi:[1,0]
	s_nop 1
	v_mfma_f32_16x16x32_bf16 v[24:27], v[40:43], v[234:237], v[24:27]
	s_waitcnt lgkmcnt(4)
	v_pk_mul_f32 v[30:31], v[30:31], v[224:225] op_sel:[0,1] op_sel_hi:[1,1]
	v_pk_mul_f32 v[28:29], v[28:29], v[224:225] op_sel:[0,1] op_sel_hi:[1,1]
	s_nop 1
	v_mfma_f32_16x16x32_bf16 v[28:31], v[40:43], v[238:241], v[28:31]
	s_waitcnt lgkmcnt(2)
	v_pk_mul_f32 v[34:35], v[34:35], v[250:251] op_sel_hi:[1,0]
	v_pk_mul_f32 v[32:33], v[32:33], v[250:251] op_sel_hi:[1,0]
	s_nop 1
	v_mfma_f32_16x16x32_bf16 v[32:35], v[40:43], v[242:245], v[32:35]
	s_waitcnt lgkmcnt(0)
	v_pk_mul_f32 v[6:7], v[6:7], v[250:251] op_sel:[0,1] op_sel_hi:[1,1]
	v_pk_mul_f32 v[4:5], v[4:5], v[250:251] op_sel:[0,1] op_sel_hi:[1,1]
	v_cvt_pk_bf16_f32 v0, v8, s0
	ds_write_b16 v124, v0 offset:37888
	v_cvt_pk_bf16_f32 v0, v9, s0
	ds_write_b16 v124, v0 offset:38160
	v_cvt_pk_bf16_f32 v0, v10, s0
	ds_write_b16 v125, v0 offset:37888
	v_cvt_pk_bf16_f32 v0, v11, s0
	ds_write_b16 v125, v0 offset:38160
	v_cvt_pk_bf16_f32 v0, v12, s0
	ds_write_b16 v124, v0 offset:37920
	v_cvt_pk_bf16_f32 v0, v13, s0
	ds_write_b16 v124, v0 offset:38192
	v_cvt_pk_bf16_f32 v0, v14, s0
	ds_write_b16 v125, v0 offset:37920
	v_cvt_pk_bf16_f32 v0, v15, s0
	ds_write_b16 v125, v0 offset:38192
	v_cvt_pk_bf16_f32 v0, v16, s0
	ds_write_b16 v124, v0 offset:37952
	v_cvt_pk_bf16_f32 v0, v17, s0
	ds_write_b16 v124, v0 offset:38224
	v_cvt_pk_bf16_f32 v0, v18, s0
	ds_write_b16 v125, v0 offset:37952
	v_cvt_pk_bf16_f32 v0, v19, s0
	ds_write_b16 v125, v0 offset:38224
	v_cvt_pk_bf16_f32 v0, v20, s0
	ds_write_b16 v124, v0 offset:37984
	v_cvt_pk_bf16_f32 v0, v21, s0
	ds_write_b16 v124, v0 offset:38256
	v_cvt_pk_bf16_f32 v0, v22, s0
	ds_write_b16 v125, v0 offset:37984
	v_cvt_pk_bf16_f32 v0, v23, s0
	ds_write_b16 v125, v0 offset:38256
	v_cvt_pk_bf16_f32 v0, v24, s0
	ds_write_b16 v124, v0 offset:38016
	v_cvt_pk_bf16_f32 v0, v25, s0
	ds_write_b16 v124, v0 offset:38288
	v_cvt_pk_bf16_f32 v0, v26, s0
	ds_write_b16 v125, v0 offset:38016
	v_cvt_pk_bf16_f32 v0, v27, s0
	ds_write_b16 v125, v0 offset:38288
	v_cvt_pk_bf16_f32 v0, v28, s0
	ds_write_b16 v124, v0 offset:38048
	v_cvt_pk_bf16_f32 v0, v29, s0
	ds_write_b16 v124, v0 offset:38320
	v_cvt_pk_bf16_f32 v0, v30, s0
	ds_write_b16 v125, v0 offset:38048
	v_cvt_pk_bf16_f32 v0, v31, s0
	v_mfma_f32_16x16x32_bf16 v[4:7], v[40:43], v[246:249], v[4:7]
	ds_write_b16 v125, v0 offset:38320
	v_cvt_pk_bf16_f32 v0, v32, s0
	ds_write_b16 v124, v0 offset:38080
	v_cvt_pk_bf16_f32 v0, v33, s0
	ds_write_b16 v124, v0 offset:38352
	v_cvt_pk_bf16_f32 v0, v34, s0
	ds_write_b16 v125, v0 offset:38080
	v_cvt_pk_bf16_f32 v0, v35, s0
	ds_write_b16 v125, v0 offset:38352
	v_cvt_pk_bf16_f32 v0, v4, s0
	ds_write_b16 v124, v0 offset:38112
	v_cvt_pk_bf16_f32 v0, v5, s0
	ds_write_b16 v124, v0 offset:38384
	v_cvt_pk_bf16_f32 v0, v6, s0
	ds_write_b16 v125, v0 offset:38112
	v_cvt_pk_bf16_f32 v0, v7, s0
	ds_write_b16 v125, v0 offset:38384
	s_waitcnt lgkmcnt(0)
	s_mov_b64 s[0:1], 0x10000
	v_lshl_add_u64 v[84:85], v[84:85], 0, s[0:1]
	v_lshl_add_u64 v[86:87], v[86:87], 0, s[0:1]
	s_mov_b64 s[0:1], 0x38000
	v_lshl_add_u64 v[88:89], v[88:89], 0, s[0:1]
	v_lshl_add_u64 v[90:91], v[90:91], 0, s[0:1]
	v_lshl_add_u64 v[92:93], v[92:93], 0, s[0:1]
	s_cbranch_scc1 .LBB0_247
